# dn_prep step 1: all 24 conv-weight quads preloaded at the top of the step (registers unused in step 1) instead of 12 serialized load/wait pairs
# speedup vs baseline: 1.0101x; 1.0101x over previous
; DI void unpack8(u32x4 w, float* f) { f[0] = bflo(w.x); f[1] = bfhi(w.x); f[2] = bflo(w.y); f[3] = bfhi(w.y); f[4] = bflo(w.z); f[5] = bfhi(w.z); f[6] = bflo(w.w); f[7] = bfhi(w.w); }
; DI void dn_prep_item(const Params& p, int l, int item, int next_item, u32x4 (&pre)[12], unsigned char* lds, int tid) {
;     ...
;     const float* cw = p.in[12] + (size_t)l * 4 * 1536;
;     float da_raw = 0.f, db_raw = 0.f, dtb = 0.f, alog = 0.f;
;     if (tid < 64) { const size_t tok = (size_t)b * SEQL + n * 64 + tid; da_raw = DAB[tok * 16 + h]; db_raw = DAB[tok * 16 + 8 + h]; dtb = p.in[14][l * 8 + h]; alog = p.in[13][l * 8 + h]; }
;     {
;         const int i = tid >> 3, d0 = (tid & 7) * 8;
; #pragma unroll
;         for (int mat = 0; mat < 3; ++mat) { const int col = mat * 512 + h * 64 + d0; float a[8];
; #pragma unroll
;             for (int e = 0; e < 8; ++e) a[e] = 0.f;
; #pragma unroll
;             for (int j = 0; j < 4; ++j) { const int t = n * 64 + i - 3 + j;
;                 if (t >= 0) { float xv[8]; unpack8(pre[mat * 4 + j], xv);
;                     const f32x4 w0 = *(const f32x4*)(cw + j * 1536 + col), w1 = *(const f32x4*)(cw + j * 1536 + col + 4);
; #pragma unroll
;                     for (int e = 0; e < 4; ++e) { a[e] += w0[e] * xv[e]; a[4 + e] += w1[e] * xv[4 + e]; } } }
.LBB0_285:
	s_or_b64 exec, exec, s[10:11]
	v_lshlrev_b32_e32 v56, 3, v54
	s_mul_i32 s5, s20, 0x6000
	v_ashrrev_i32_e32 v77, 3, v54
	v_and_b32_e32 v82, 56, v56
	s_waitcnt lgkmcnt(0)
	s_add_u32 s8, s8, s5
	s_mul_hi_i32 s5, s20, 0x6000
	v_add_u32_e32 v83, v1, v77
	v_lshlrev_b32_e32 v1, 2, v82
	s_addc_u32 s9, s9, s5
	v_lshl_or_b32 v164, s4, 8, v1
	v_lshl_add_u64 v[56:57], s[8:9], 0, v[164:165]
	s_mov_b64 s[22:23], 0x3000
	v_lshl_add_u64 v[190:191], v[56:57], 0, s[22:23]
	s_mov_b64 s[22:23], 0x1000
	v_lshl_add_u64 v[192:193], v[56:57], 0, s[22:23]
	s_mov_b64 s[22:23], 0x4000
	v_lshl_add_u64 v[194:195], v[56:57], 0, s[22:23]
	s_mov_b64 s[22:23], 0x2000
	v_lshl_add_u64 v[196:197], v[56:57], 0, s[22:23]
	s_mov_b64 s[22:23], 0x5000
	v_lshl_add_u64 v[198:199], v[56:57], 0, s[22:23]
	global_load_dwordx4 v[88:91], v[56:57], off offset:16
	global_load_dwordx4 v[92:95], v[56:57], off
	global_load_dwordx4 v[96:99], v[190:191], off
	global_load_dwordx4 v[100:103], v[190:191], off offset:16
	global_load_dwordx4 v[104:107], v[192:193], off offset:2048
	global_load_dwordx4 v[108:111], v[192:193], off offset:2064
	global_load_dwordx4 v[112:115], v[194:195], off offset:2048
	global_load_dwordx4 v[116:119], v[194:195], off offset:2064
	global_load_dwordx4 v[120:123], v[56:57], off offset:2064
	global_load_dwordx4 v[124:127], v[56:57], off offset:2048
	global_load_dwordx4 v[128:131], v[190:191], off offset:2048
	global_load_dwordx4 v[132:135], v[190:191], off offset:2064
	global_load_dwordx4 v[136:139], v[196:197], off
	global_load_dwordx4 v[140:143], v[196:197], off offset:16
	global_load_dwordx4 v[144:147], v[198:199], off
	global_load_dwordx4 v[148:151], v[198:199], off offset:16
	global_load_dwordx4 v[152:155], v[192:193], off
	global_load_dwordx4 v[156:159], v[192:193], off offset:16
	global_load_dwordx4 v[160:163], v[194:195], off
	global_load_dwordx4 v[170:173], v[194:195], off offset:16
	global_load_dwordx4 v[174:177], v[196:197], off offset:2048
	global_load_dwordx4 v[178:181], v[196:197], off offset:2064
	global_load_dwordx4 v[182:185], v[198:199], off offset:2048
	global_load_dwordx4 v[186:189], v[198:199], off offset:2064
	v_cmp_lt_i32_e64 s[14:15], 2, v83
	v_mov_b32_e32 v67, 0
	v_mov_b32_e32 v58, 0
	v_mov_b32_e32 v59, 0
	v_mov_b32_e32 v62, 0
	v_mov_b32_e32 v63, 0
	v_mov_b32_e32 v60, 0
	v_mov_b32_e32 v61, 0
	v_mov_b32_e32 v64, 0
	v_mov_b32_e32 v65, 0
	s_and_saveexec_b64 s[8:9], s[14:15]
	s_cbranch_execz .LBB0_289
	s_waitcnt vmcnt(0)
	v_lshlrev_b32_e32 v58, 16, v46
	v_and_b32_e32 v59, 0xffff0000, v46
	v_lshlrev_b32_e32 v60, 16, v48
	v_and_b32_e32 v61, 0xffff0000, v48
	v_lshlrev_b32_e32 v46, 16, v47
	v_and_b32_e32 v47, 0xffff0000, v47
	s_waitcnt vmcnt(0)
	v_pk_fma_f32 v[60:61], v[88:89], v[60:61], 0 op_sel_hi:[1,1,0]
	s_waitcnt vmcnt(0)
	v_pk_fma_f32 v[62:63], v[94:95], v[46:47], 0 op_sel_hi:[1,1,0]
	v_lshlrev_b32_e32 v46, 16, v49
	v_and_b32_e32 v47, 0xffff0000, v49
	v_pk_fma_f32 v[66:67], v[90:91], v[46:47], 0 op_sel_hi:[1,1,0]
	v_pk_fma_f32 v[58:59], v[92:93], v[58:59], 0 op_sel_hi:[1,1,0]
	v_mov_b32_e32 v64, v66
	v_mov_b32_e32 v65, v67
	s_or_b64 exec, exec, s[8:9]
	v_cmp_lt_i32_e64 s[8:9], 1, v83
	s_and_saveexec_b64 s[10:11], s[8:9]
	s_cbranch_execnz .LBB0_290

; DI void unpack8(u32x4 w, float* f) { f[0] = bflo(w.x); f[1] = bfhi(w.x); f[2] = bflo(w.y); f[3] = bfhi(w.y); f[4] = bflo(w.z); f[5] = bfhi(w.z); f[6] = bflo(w.w); f[7] = bfhi(w.w); }
; DI void dn_prep_item(const Params& p, int l, int item, int next_item, u32x4 (&pre)[12], unsigned char* lds, int tid) {
;     ...
;             for (int j = 0; j < 4; ++j) { const int t = n * 64 + i - 3 + j;
;                 if (t >= 0) { float xv[8]; unpack8(pre[mat * 4 + j], xv);
;                     const f32x4 w0 = *(const f32x4*)(cw + j * 1536 + col), w1 = *(const f32x4*)(cw + j * 1536 + col + 4);
; #pragma unroll
;                     for (int e = 0; e < 4; ++e) { a[e] += w0[e] * xv[e]; a[4 + e] += w1[e] * xv[4 + e]; } } }
.LBB0_288:
	s_mov_b64 s[22:23], 0x3000
	s_waitcnt vmcnt(0)
	v_add_co_u32_e32 v42, vcc, 0x3000, v56
	s_waitcnt vmcnt(0)
	v_lshl_add_u64 v[46:47], v[56:57], 0, s[22:23]
	v_addc_co_u32_e32 v43, vcc, 0, v57, vcc
	s_nop 0
	v_lshlrev_b32_e32 v66, 16, v38
	v_and_b32_e32 v67, 0xffff0000, v38
	v_lshlrev_b32_e32 v38, 16, v39
	v_and_b32_e32 v39, 0xffff0000, v39
	s_waitcnt vmcnt(0)
	v_pk_fma_f32 v[58:59], v[96:97], v[66:67], v[58:59]
	v_lshlrev_b32_e32 v42, 16, v40
	v_and_b32_e32 v43, 0xffff0000, v40
	v_pk_fma_f32 v[62:63], v[98:99], v[38:39], v[62:63]
	v_lshlrev_b32_e32 v38, 16, v41
	v_and_b32_e32 v39, 0xffff0000, v41
	s_waitcnt vmcnt(0)
	v_pk_fma_f32 v[60:61], v[100:101], v[42:43], v[60:61]
	v_pk_fma_f32 v[64:65], v[102:103], v[38:39], v[64:65]
	s_or_b64 exec, exec, s[12:13]
	v_cmp_lt_i32_e64 s[12:13], -1, v83
	s_and_saveexec_b64 s[30:31], s[12:13]
	s_cbranch_execnz .LBB0_292
	s_branch .LBB0_293

; DI void unpack8(u32x4 w, float* f) { f[0] = bflo(w.x); f[1] = bfhi(w.x); f[2] = bflo(w.y); f[3] = bfhi(w.y); f[4] = bflo(w.z); f[5] = bfhi(w.z); f[6] = bflo(w.w); f[7] = bfhi(w.w); }
; DI void dn_prep_item(const Params& p, int l, int item, int next_item, u32x4 (&pre)[12], unsigned char* lds, int tid) {
;     ...
;             for (int j = 0; j < 4; ++j) { const int t = n * 64 + i - 3 + j;
;                 if (t >= 0) { float xv[8]; unpack8(pre[mat * 4 + j], xv);
;                     const f32x4 w0 = *(const f32x4*)(cw + j * 1536 + col), w1 = *(const f32x4*)(cw + j * 1536 + col + 4);
; #pragma unroll
;                     for (int e = 0; e < 4; ++e) { a[e] += w0[e] * xv[e]; a[4 + e] += w1[e] * xv[4 + e]; } } }
.LBB0_290:
	s_waitcnt vmcnt(0)
	v_add_co_u32_e32 v46, vcc, 0x1000, v56
	s_mov_b64 s[12:13], 0x1800
	s_nop 0
	v_addc_co_u32_e32 v47, vcc, 0, v57, vcc
	v_lshl_add_u64 v[64:65], v[56:57], 0, s[12:13]
	s_nop 0
	v_lshlrev_b32_e32 v64, 16, v42
	v_and_b32_e32 v65, 0xffff0000, v42
	v_lshlrev_b32_e32 v42, 16, v43
	v_and_b32_e32 v43, 0xffff0000, v43
	s_waitcnt vmcnt(0)
	v_pk_fma_f32 v[58:59], v[104:105], v[64:65], v[58:59]
	v_lshlrev_b32_e32 v46, 16, v44
	v_and_b32_e32 v47, 0xffff0000, v44
	v_pk_fma_f32 v[62:63], v[106:107], v[42:43], v[62:63]
	v_lshlrev_b32_e32 v42, 16, v45
	v_and_b32_e32 v43, 0xffff0000, v45
	s_waitcnt vmcnt(0)
	v_pk_fma_f32 v[60:61], v[108:109], v[46:47], v[60:61]
	v_pk_fma_f32 v[64:65], v[110:111], v[42:43], v[66:67]
	s_or_b64 exec, exec, s[10:11]
	v_cmp_lt_i32_e64 s[10:11], 0, v83
	s_and_saveexec_b64 s[12:13], s[10:11]
	s_cbranch_execnz .LBB0_288

; DI unsigned pk2(float lo, float hi) { f32x2_t v = {lo, hi}; bf16x2_t b = __builtin_convertvector(v, bf16x2_t); return __builtin_bit_cast(unsigned, b); }
; DI float silu_f(float x) { return x * __builtin_amdgcn_rcpf(1.f + __builtin_amdgcn_exp2f(-1.4426950408889634f * x)); }
; DI void unpack8(u32x4 w, float* f) { f[0] = bflo(w.x); f[1] = bfhi(w.x); f[2] = bflo(w.y); f[3] = bfhi(w.y); f[4] = bflo(w.z); f[5] = bfhi(w.z); f[6] = bflo(w.w); f[7] = bfhi(w.w); }
; DI void dn_prep_item(const Params& p, int l, int item, int next_item, u32x4 (&pre)[12], unsigned char* lds, int tid) {
;     ...
;             for (int j = 0; j < 4; ++j) { const int t = n * 64 + i - 3 + j;
;                 if (t >= 0) { float xv[8]; unpack8(pre[mat * 4 + j], xv);
;                     const f32x4 w0 = *(const f32x4*)(cw + j * 1536 + col), w1 = *(const f32x4*)(cw + j * 1536 + col + 4);
; #pragma unroll
;                     for (int e = 0; e < 4; ++e) { a[e] += w0[e] * xv[e]; a[4 + e] += w1[e] * xv[4 + e]; } } }
;             float ss = 0.f;
; #pragma unroll
;             for (int e = 0; e < 8; ++e) { a[e] = silu_f(a[e]); ss += a[e] * a[e]; }
;             float sc = 1.f;
;             if (mat < 2) { ss += __shfl_xor(ss, 1); ss += __shfl_xor(ss, 2); ss += __shfl_xor(ss, 4); sc = rsqrtf(ss + EPSF) * (mat == 0 ? 0.125f : 1.f); }
;             float* dst = (mat == 0 ? Qs : (mat == 1 ? Ks : Vs)) + i * 65 + d0;
; #pragma unroll
;             for (int e = 0; e < 8; ++e) { a[e] *= sc; dst[e] = a[e]; }
;             if (mat < 2) { float hf[8], lo[8]; u32x4 wh, wl;
;                 wh.x = pk2(a[0], a[1]); wh.y = pk2(a[2], a[3]); wh.z = pk2(a[4], a[5]); wh.w = pk2(a[6], a[7]); unpack8(wh, hf);
; #pragma unroll
;                 for (int e = 0; e < 8; ++e) lo[e] = a[e] - hf[e];
;                 wl.x = pk2(lo[0], lo[1]); wl.y = pk2(lo[2], lo[3]); wl.z = pk2(lo[4], lo[5]); wl.w = pk2(lo[6], lo[7]);
;                 *(u32x4*)((mat == 0 ? QH : KH) + i * 72 + d0) = wh; *(u32x4*)((mat == 0 ? QL : KL) + i * 72 + d0) = wl; } }
.LBB0_292:
	s_mov_b64 s[22:23], 0x4800
	s_waitcnt vmcnt(0)
	v_add_co_u32_e32 v38, vcc, 0x4000, v56
	s_waitcnt vmcnt(0)
	v_lshl_add_u64 v[42:43], v[56:57], 0, s[22:23]
	v_addc_co_u32_e32 v39, vcc, 0, v57, vcc
	s_nop 0
	s_waitcnt vmcnt(0)
	v_lshlrev_b32_e32 v46, 16, v34
	v_and_b32_e32 v47, 0xffff0000, v34
	v_lshlrev_b32_e32 v34, 16, v35
	v_and_b32_e32 v35, 0xffff0000, v35
	s_waitcnt vmcnt(0)
	v_pk_fma_f32 v[58:59], v[112:113], v[46:47], v[58:59]
	v_lshlrev_b32_e32 v38, 16, v36
	v_and_b32_e32 v39, 0xffff0000, v36
	v_pk_fma_f32 v[62:63], v[114:115], v[34:35], v[62:63]
	v_lshlrev_b32_e32 v34, 16, v37
	v_and_b32_e32 v35, 0xffff0000, v37
	s_waitcnt vmcnt(0)
	v_pk_fma_f32 v[60:61], v[116:117], v[38:39], v[60:61]
	v_pk_fma_f32 v[64:65], v[118:119], v[34:35], v[64:65]
.LBB0_293:
	s_or_b64 exec, exec, s[30:31]
	s_waitcnt vmcnt(0)
	v_mul_f32_e32 v34, 0xbfb8aa3b, v58
	v_exp_f32_e32 v34, v34
	v_mul_f32_e32 v35, 0xbfb8aa3b, v59
	v_exp_f32_e32 v35, v35
	v_mul_f32_e32 v37, 0xbfb8aa3b, v63
	v_add_f32_e32 v34, 1.0, v34
	v_rcp_f32_e32 v36, v34
	v_mul_f32_e32 v34, 0xbfb8aa3b, v62
	v_exp_f32_e32 v34, v34
	s_waitcnt vmcnt(0)
	v_exp_f32_e32 v39, v37
	v_add_f32_e32 v35, 1.0, v35
	v_rcp_f32_e32 v37, v35
	v_add_f32_e32 v34, 1.0, v34
	v_mul_f32_e32 v35, 0xbfb8aa3b, v60
	v_rcp_f32_e32 v38, v34
	v_add_f32_e32 v34, 1.0, v39
	v_exp_f32_e32 v35, v35
	v_mul_f32_e32 v39, 0xbfb8aa3b, v61
	v_exp_f32_e32 v41, v39
	v_rcp_f32_e32 v39, v34
	v_add_f32_e32 v34, 1.0, v35
	v_mul_f32_e32 v35, 0xbfb8aa3b, v64
	v_rcp_f32_e32 v40, v34
	v_add_f32_e32 v34, 1.0, v41
	v_exp_f32_e32 v35, v35
	v_mul_f32_e32 v41, 0xbfb8aa3b, v65
	s_waitcnt vmcnt(0)
	v_exp_f32_e32 v43, v41
	v_rcp_f32_e32 v41, v34
	v_add_f32_e32 v34, 1.0, v35
	v_rcp_f32_e32 v42, v34
	v_add_f32_e32 v34, 1.0, v43
	v_and_b32_e32 v35, 64, v206
	v_rcp_f32_e32 v43, v34
	v_xor_b32_e32 v34, 1, v206
	v_add_u32_e32 v66, 64, v35
	v_cmp_lt_i32_e32 vcc, v34, v66
	v_pk_mul_f32 v[44:45], v[58:59], v[36:37]
	v_pk_mul_f32 v[58:59], v[62:63], v[38:39]
	v_cndmask_b32_e32 v34, v206, v34, vcc
	v_pk_mul_f32 v[36:37], v[44:45], v[44:45]
	s_waitcnt vmcnt(0)
	v_lshlrev_b32_e32 v46, 2, v34
	v_pk_mul_f32 v[38:39], v[58:59], v[58:59]
	v_add_f32_e32 v34, v36, v37
	v_pk_mul_f32 v[40:41], v[60:61], v[40:41]
	v_add_f32_e32 v34, v38, v34
	v_pk_mul_f32 v[48:49], v[40:41], v[40:41]
	v_add_f32_e32 v34, v39, v34
	v_pk_mul_f32 v[42:43], v[64:65], v[42:43]
	v_add_f32_e32 v34, v48, v34
	v_pk_mul_f32 v[60:61], v[42:43], v[42:43]
	v_add_f32_e32 v34, v49, v34
	v_add_f32_e32 v34, v60, v34
	v_add_f32_e32 v34, v61, v34
	ds_bpermute_b32 v36, v46, v34
	v_xor_b32_e32 v37, 2, v206
	v_cmp_lt_i32_e32 vcc, v37, v66
	s_movk_i32 s5, 0x48
	v_mul_lo_u32 v49, v77, s5
	v_cndmask_b32_e32 v37, v206, v37, vcc
	v_lshlrev_b32_e32 v47, 2, v37
	s_waitcnt lgkmcnt(0)
	v_add_f32_e32 v34, v34, v36
	ds_bpermute_b32 v36, v47, v34
	v_xor_b32_e32 v37, 4, v206
	v_cmp_lt_i32_e32 vcc, v37, v66
	s_movk_i32 s5, 0x104
	v_lshlrev_b32_e32 v49, 1, v49
	v_cndmask_b32_e32 v37, v206, v37, vcc
	v_lshlrev_b32_e32 v48, 2, v37
	s_waitcnt lgkmcnt(0)
	v_add_f32_e32 v34, v34, v36
	ds_bpermute_b32 v36, v48, v34
	s_waitcnt lgkmcnt(0)
	v_add_f32_e32 v34, v34, v36
	v_add_f32_e32 v34, 0x358637bd, v34
	v_mul_f32_e32 v36, 0x4b800000, v34
	v_cmp_gt_f32_e32 vcc, s57, v34
	s_nop 1
	v_cndmask_b32_e32 v34, v34, v36, vcc
	v_rsq_f32_e32 v34, v34
	v_mul_lo_u32 v36, v77, s5
	v_add3_u32 v1, v168, v36, v1
	v_mul_f32_e32 v36, 0x45800000, v34
	v_cndmask_b32_e32 v34, v34, v36, vcc
	v_mul_f32_e32 v34, 0x3e000000, v34
	v_pk_mul_f32 v[36:37], v[44:45], v[34:35] op_sel_hi:[1,0]
	ds_write2_b32 v1, v36, v37 offset1:1
	v_pk_mul_f32 v[38:39], v[58:59], v[34:35] op_sel_hi:[1,0]
	v_pk_mul_f32 v[60:61], v[40:41], v[34:35] op_sel_hi:[1,0]
	v_cvt_pk_bf16_f32 v36, v36, v37
	ds_write2_b32 v1, v38, v39 offset0:2 offset1:3
	ds_write2_b32 v1, v60, v61 offset0:4 offset1:5
	v_cvt_pk_bf16_f32 v37, v38, v39
	v_cvt_pk_bf16_f32 v38, v60, v61
	v_lshlrev_b32_e32 v60, 16, v36
	v_and_b32_e32 v61, 0xffff0000, v36
	v_pk_mul_f32 v[62:63], v[42:43], v[34:35] op_sel_hi:[1,0]
	v_pk_fma_f32 v[44:45], v[44:45], v[34:35], v[60:61] op_sel_hi:[1,0,1] neg_lo:[0,0,1] neg_hi:[0,0,1]
	v_lshlrev_b32_e32 v60, 16, v37
	v_and_b32_e32 v61, 0xffff0000, v37
	v_cvt_pk_bf16_f32 v39, v62, v63
	v_pk_fma_f32 v[58:59], v[58:59], v[34:35], v[60:61] op_sel_hi:[1,0,1] neg_lo:[0,0,1] neg_hi:[0,0,1]
	v_lshlrev_b32_e32 v60, 16, v38
	v_and_b32_e32 v61, 0xffff0000, v38
	v_pk_fma_f32 v[60:61], v[40:41], v[34:35], v[60:61] op_sel_hi:[1,0,1] neg_lo:[0,0,1] neg_hi:[0,0,1]
	v_lshlrev_b32_e32 v40, 16, v39
	v_and_b32_e32 v41, 0xffff0000, v39
	ds_write2_b32 v1, v62, v63 offset0:6 offset1:7
	v_pk_fma_f32 v[62:63], v[42:43], v[34:35], v[40:41] op_sel_hi:[1,0,1] neg_lo:[0,0,1] neg_hi:[0,0,1]
	v_lshlrev_b32_e32 v34, 1, v82
	v_cvt_pk_bf16_f32 v40, v44, v45
	v_add3_u32 v44, v73, v49, v34
	v_cvt_pk_bf16_f32 v41, v58, v59
	v_cvt_pk_bf16_f32 v42, v60, v61
	v_cvt_pk_bf16_f32 v43, v62, v63
	ds_write_b128 v44, v[36:39]
	v_add3_u32 v36, v74, v49, v34
	v_mov_b32_e32 v44, 0
	ds_write_b128 v36, v[40:43]
	v_mov_b32_e32 v45, 0
	v_mov_b32_e32 v38, 0
	v_mov_b32_e32 v39, 0
	v_mov_b32_e32 v40, 0
	v_mov_b32_e32 v41, v44
	v_mov_b32_e32 v36, v44
	v_mov_b32_e32 v37, v44
	v_mov_b32_e32 v42, 0
	v_mov_b32_e32 v43, 0
	s_and_saveexec_b64 s[30:31], s[14:15]
	s_cbranch_execz .LBB0_297
	v_lshlrev_b32_e32 v36, 16, v30
	v_and_b32_e32 v37, 0xffff0000, v30
	v_lshlrev_b32_e32 v30, 16, v31
	v_and_b32_e32 v31, 0xffff0000, v31
	s_waitcnt vmcnt(0)
	v_pk_fma_f32 v[38:39], v[124:125], v[36:37], 0 op_sel_hi:[1,1,0]
	v_lshlrev_b32_e32 v36, 16, v32
	v_and_b32_e32 v37, 0xffff0000, v32
	v_pk_fma_f32 v[36:37], v[120:121], v[36:37], 0 op_sel_hi:[1,1,0]
	v_pk_fma_f32 v[40:41], v[126:127], v[30:31], 0 op_sel_hi:[1,1,0]
	v_lshlrev_b32_e32 v30, 16, v33
	v_and_b32_e32 v31, 0xffff0000, v33
	v_pk_fma_f32 v[44:45], v[122:123], v[30:31], 0 op_sel_hi:[1,1,0]
	s_nop 0
	v_mov_b32_e32 v42, v44
	v_mov_b32_e32 v43, v45
	s_or_b64 exec, exec, s[30:31]
	s_and_saveexec_b64 s[30:31], s[8:9]
	s_cbranch_execnz .LBB0_298

; DI void unpack8(u32x4 w, float* f) { f[0] = bflo(w.x); f[1] = bfhi(w.x); f[2] = bflo(w.y); f[3] = bfhi(w.y); f[4] = bflo(w.z); f[5] = bfhi(w.z); f[6] = bflo(w.w); f[7] = bfhi(w.w); }
; DI void dn_prep_item(const Params& p, int l, int item, int next_item, u32x4 (&pre)[12], unsigned char* lds, int tid) {
;     ...
;             for (int j = 0; j < 4; ++j) { const int t = n * 64 + i - 3 + j;
;                 if (t >= 0) { float xv[8]; unpack8(pre[mat * 4 + j], xv);
;                     const f32x4 w0 = *(const f32x4*)(cw + j * 1536 + col), w1 = *(const f32x4*)(cw + j * 1536 + col + 4);
; #pragma unroll
;                     for (int e = 0; e < 4; ++e) { a[e] += w0[e] * xv[e]; a[4 + e] += w1[e] * xv[4 + e]; } } }
.LBB0_296:
	s_mov_b64 s[22:23], 0x3800
	v_add_co_u32_e32 v26, vcc, 0x3000, v56
	v_lshl_add_u64 v[30:31], v[56:57], 0, s[22:23]
	s_nop 0
	v_addc_co_u32_e32 v27, vcc, 0, v57, vcc
	s_nop 0
	v_lshlrev_b32_e32 v44, 16, v22
	v_and_b32_e32 v45, 0xffff0000, v22
	v_lshlrev_b32_e32 v22, 16, v23
	v_and_b32_e32 v23, 0xffff0000, v23
	s_waitcnt vmcnt(0)
	v_pk_fma_f32 v[38:39], v[128:129], v[44:45], v[38:39]
	v_lshlrev_b32_e32 v26, 16, v24
	v_and_b32_e32 v27, 0xffff0000, v24
	v_pk_fma_f32 v[40:41], v[130:131], v[22:23], v[40:41]
	v_lshlrev_b32_e32 v22, 16, v25
	v_and_b32_e32 v23, 0xffff0000, v25
	s_waitcnt vmcnt(0)
	v_pk_fma_f32 v[36:37], v[132:133], v[26:27], v[36:37]
	v_pk_fma_f32 v[42:43], v[134:135], v[22:23], v[42:43]
	s_or_b64 exec, exec, s[30:31]
	s_and_saveexec_b64 s[30:31], s[12:13]
	s_cbranch_execnz .LBB0_300
	s_branch .LBB0_301

; DI void unpack8(u32x4 w, float* f) { f[0] = bflo(w.x); f[1] = bfhi(w.x); f[2] = bflo(w.y); f[3] = bfhi(w.y); f[4] = bflo(w.z); f[5] = bfhi(w.z); f[6] = bflo(w.w); f[7] = bfhi(w.w); }
; DI void dn_prep_item(const Params& p, int l, int item, int next_item, u32x4 (&pre)[12], unsigned char* lds, int tid) {
;     ...
;             for (int j = 0; j < 4; ++j) { const int t = n * 64 + i - 3 + j;
;                 if (t >= 0) { float xv[8]; unpack8(pre[mat * 4 + j], xv);
;                     const f32x4 w0 = *(const f32x4*)(cw + j * 1536 + col), w1 = *(const f32x4*)(cw + j * 1536 + col + 4);
; #pragma unroll
;                     for (int e = 0; e < 4; ++e) { a[e] += w0[e] * xv[e]; a[4 + e] += w1[e] * xv[4 + e]; } } }
.LBB0_298:
	v_add_co_u32_e32 v30, vcc, 0x2000, v56
	s_mov_b64 s[22:23], 0x2000
	s_nop 0
	v_addc_co_u32_e32 v31, vcc, 0, v57, vcc
	v_lshl_add_u64 v[42:43], v[56:57], 0, s[22:23]
	s_nop 0
	v_lshlrev_b32_e32 v42, 16, v26
	v_and_b32_e32 v43, 0xffff0000, v26
	v_lshlrev_b32_e32 v26, 16, v27
	v_and_b32_e32 v27, 0xffff0000, v27
	s_waitcnt vmcnt(0)
	v_pk_fma_f32 v[38:39], v[136:137], v[42:43], v[38:39]
	v_lshlrev_b32_e32 v30, 16, v28
	v_and_b32_e32 v31, 0xffff0000, v28
	v_pk_fma_f32 v[40:41], v[138:139], v[26:27], v[40:41]
	v_lshlrev_b32_e32 v26, 16, v29
	v_and_b32_e32 v27, 0xffff0000, v29
	s_waitcnt vmcnt(0)
	v_pk_fma_f32 v[36:37], v[140:141], v[30:31], v[36:37]
	v_pk_fma_f32 v[42:43], v[142:143], v[26:27], v[44:45]
	s_or_b64 exec, exec, s[30:31]
	s_and_saveexec_b64 s[30:31], s[10:11]
	s_cbranch_execnz .LBB0_296

; DI unsigned pk2(float lo, float hi) { f32x2_t v = {lo, hi}; bf16x2_t b = __builtin_convertvector(v, bf16x2_t); return __builtin_bit_cast(unsigned, b); }
; DI float silu_f(float x) { return x * __builtin_amdgcn_rcpf(1.f + __builtin_amdgcn_exp2f(-1.4426950408889634f * x)); }
; DI void unpack8(u32x4 w, float* f) { f[0] = bflo(w.x); f[1] = bfhi(w.x); f[2] = bflo(w.y); f[3] = bfhi(w.y); f[4] = bflo(w.z); f[5] = bfhi(w.z); f[6] = bflo(w.w); f[7] = bfhi(w.w); }
; DI void dn_prep_item(const Params& p, int l, int item, int next_item, u32x4 (&pre)[12], unsigned char* lds, int tid) {
;     ...
;             for (int j = 0; j < 4; ++j) { const int t = n * 64 + i - 3 + j;
;                 if (t >= 0) { float xv[8]; unpack8(pre[mat * 4 + j], xv);
;                     const f32x4 w0 = *(const f32x4*)(cw + j * 1536 + col), w1 = *(const f32x4*)(cw + j * 1536 + col + 4);
; #pragma unroll
;                     for (int e = 0; e < 4; ++e) { a[e] += w0[e] * xv[e]; a[4 + e] += w1[e] * xv[4 + e]; } } }
;             float ss = 0.f;
; #pragma unroll
;             for (int e = 0; e < 8; ++e) { a[e] = silu_f(a[e]); ss += a[e] * a[e]; }
;             float sc = 1.f;
;             if (mat < 2) { ss += __shfl_xor(ss, 1); ss += __shfl_xor(ss, 2); ss += __shfl_xor(ss, 4); sc = rsqrtf(ss + EPSF) * (mat == 0 ? 0.125f : 1.f); }
;             float* dst = (mat == 0 ? Qs : (mat == 1 ? Ks : Vs)) + i * 65 + d0;
; #pragma unroll
;             for (int e = 0; e < 8; ++e) { a[e] *= sc; dst[e] = a[e]; }
;             if (mat < 2) { float hf[8], lo[8]; u32x4 wh, wl;
;                 wh.x = pk2(a[0], a[1]); wh.y = pk2(a[2], a[3]); wh.z = pk2(a[4], a[5]); wh.w = pk2(a[6], a[7]); unpack8(wh, hf);
; #pragma unroll
;                 for (int e = 0; e < 8; ++e) lo[e] = a[e] - hf[e];
;                 wl.x = pk2(lo[0], lo[1]); wl.y = pk2(lo[2], lo[3]); wl.z = pk2(lo[4], lo[5]); wl.w = pk2(lo[6], lo[7]);
;                 *(u32x4*)((mat == 0 ? QH : KH) + i * 72 + d0) = wh; *(u32x4*)((mat == 0 ? QL : KL) + i * 72 + d0) = wl; } }
.LBB0_300:
	s_mov_b64 s[22:23], 0x5000
	v_add_co_u32_e32 v22, vcc, 0x5000, v56
	v_lshl_add_u64 v[26:27], v[56:57], 0, s[22:23]
	s_nop 0
	v_addc_co_u32_e32 v23, vcc, 0, v57, vcc
	s_nop 0
	v_lshlrev_b32_e32 v30, 16, v18
	v_and_b32_e32 v31, 0xffff0000, v18
	v_lshlrev_b32_e32 v18, 16, v19
	v_and_b32_e32 v19, 0xffff0000, v19
	s_waitcnt vmcnt(0)
	v_pk_fma_f32 v[38:39], v[144:145], v[30:31], v[38:39]
	v_lshlrev_b32_e32 v22, 16, v20
	v_and_b32_e32 v23, 0xffff0000, v20
	v_pk_fma_f32 v[40:41], v[146:147], v[18:19], v[40:41]
	v_lshlrev_b32_e32 v18, 16, v21
	v_and_b32_e32 v19, 0xffff0000, v21
	s_waitcnt vmcnt(0)
	v_pk_fma_f32 v[36:37], v[148:149], v[22:23], v[36:37]
	v_pk_fma_f32 v[42:43], v[150:151], v[18:19], v[42:43]
.LBB0_301:
	s_or_b64 exec, exec, s[30:31]
	v_mul_f32_e32 v18, 0xbfb8aa3b, v38
	v_mul_f32_e32 v19, 0xbfb8aa3b, v39
	v_exp_f32_e32 v18, v18
	v_exp_f32_e32 v19, v19
	v_mul_f32_e32 v20, 0xbfb8aa3b, v40
	v_mul_f32_e32 v21, 0xbfb8aa3b, v41
	v_exp_f32_e32 v20, v20
	v_exp_f32_e32 v21, v21
	v_mul_f32_e32 v22, 0xbfb8aa3b, v36
	v_mul_f32_e32 v23, 0xbfb8aa3b, v37
	v_exp_f32_e32 v22, v22
	v_exp_f32_e32 v23, v23
	v_add_f32_e32 v18, 1.0, v18
	v_add_f32_e32 v19, 1.0, v19
	v_mul_f32_e32 v24, 0xbfb8aa3b, v42
	v_mul_f32_e32 v25, 0xbfb8aa3b, v43
	v_rcp_f32_e32 v18, v18
	v_rcp_f32_e32 v19, v19
	v_add_f32_e32 v20, 1.0, v20
	v_add_f32_e32 v21, 1.0, v21
	v_exp_f32_e32 v24, v24
	v_exp_f32_e32 v25, v25
	v_rcp_f32_e32 v20, v20
	v_rcp_f32_e32 v21, v21
	v_add_f32_e32 v22, 1.0, v22
	v_add_f32_e32 v23, 1.0, v23
	v_rcp_f32_e32 v22, v22
	v_rcp_f32_e32 v23, v23
	v_add_f32_e32 v24, 1.0, v24
	v_add_f32_e32 v25, 1.0, v25
	v_pk_mul_f32 v[26:27], v[38:39], v[18:19]
	v_rcp_f32_e32 v24, v24
	v_rcp_f32_e32 v25, v25
	v_pk_mul_f32 v[18:19], v[26:27], v[26:27]
	v_pk_mul_f32 v[28:29], v[40:41], v[20:21]
	v_add_f32_e32 v18, v18, v19
	v_pk_mul_f32 v[20:21], v[28:29], v[28:29]
	v_pk_mul_f32 v[22:23], v[36:37], v[22:23]
	v_add_f32_e32 v18, v20, v18
	v_pk_mul_f32 v[30:31], v[22:23], v[22:23]
	v_add_f32_e32 v18, v21, v18
	v_pk_mul_f32 v[24:25], v[42:43], v[24:25]
	v_add_f32_e32 v18, v30, v18
	v_pk_mul_f32 v[32:33], v[24:25], v[24:25]
	v_add_f32_e32 v18, v31, v18
	v_add_f32_e32 v18, v32, v18
	v_add_f32_e32 v18, v33, v18
	ds_bpermute_b32 v19, v46, v18
	v_add_u32_e32 v31, 0x4108, v1
	v_add_u32_e32 v20, 0x4100, v1
	v_add_u32_e32 v36, 0x4110, v1
	v_add_u32_e32 v38, 0x4118, v1
	s_waitcnt lgkmcnt(0)
	v_add_f32_e32 v18, v18, v19
	ds_bpermute_b32 v19, v47, v18
	s_waitcnt lgkmcnt(0)
	v_add_f32_e32 v18, v18, v19
	ds_bpermute_b32 v19, v48, v18
	s_waitcnt lgkmcnt(0)
	v_add_f32_e32 v18, v18, v19
	v_add_f32_e32 v18, 0x358637bd, v18
	v_mul_f32_e32 v19, 0x4b800000, v18
	v_cmp_gt_f32_e32 vcc, s57, v18
	s_nop 1
	v_cndmask_b32_e32 v18, v18, v19, vcc
	v_rsq_f32_e32 v18, v18
	s_nop 0
	v_mul_f32_e32 v19, 0x45800000, v18
	v_cndmask_b32_e32 v30, v18, v19, vcc
	v_pk_mul_f32 v[18:19], v[26:27], v[30:31] op_sel_hi:[1,0]
	ds_write2_b32 v20, v18, v19 offset1:1
	v_pk_mul_f32 v[20:21], v[28:29], v[30:31] op_sel_hi:[1,0]
	v_pk_mul_f32 v[32:33], v[22:23], v[30:31] op_sel_hi:[1,0]
	v_cvt_pk_bf16_f32 v18, v18, v19
	ds_write2_b32 v31, v20, v21 offset1:1
	ds_write2_b32 v36, v32, v33 offset1:1
	v_cvt_pk_bf16_f32 v19, v20, v21
	v_cvt_pk_bf16_f32 v20, v32, v33
	v_lshlrev_b32_e32 v32, 16, v18
	v_and_b32_e32 v33, 0xffff0000, v18
	v_pk_mul_f32 v[36:37], v[24:25], v[30:31] op_sel_hi:[1,0]
	v_pk_fma_f32 v[26:27], v[26:27], v[30:31], v[32:33] op_sel_hi:[1,0,1] neg_lo:[0,0,1] neg_hi:[0,0,1]
	v_lshlrev_b32_e32 v32, 16, v19
	v_and_b32_e32 v33, 0xffff0000, v19
	v_cvt_pk_bf16_f32 v21, v36, v37
	v_pk_fma_f32 v[28:29], v[28:29], v[30:31], v[32:33] op_sel_hi:[1,0,1] neg_lo:[0,0,1] neg_hi:[0,0,1]
	v_lshlrev_b32_e32 v32, 16, v20
	v_and_b32_e32 v33, 0xffff0000, v20
	v_pk_fma_f32 v[32:33], v[22:23], v[30:31], v[32:33] op_sel_hi:[1,0,1] neg_lo:[0,0,1] neg_hi:[0,0,1]
	v_lshlrev_b32_e32 v22, 16, v21
	v_and_b32_e32 v23, 0xffff0000, v21
	v_pk_fma_f32 v[30:31], v[24:25], v[30:31], v[22:23] op_sel_hi:[1,0,1] neg_lo:[0,0,1] neg_hi:[0,0,1]
	v_cvt_pk_bf16_f32 v22, v26, v27
	v_add3_u32 v26, v71, v49, v34
	ds_write2_b32 v38, v36, v37 offset1:1
	v_cvt_pk_bf16_f32 v23, v28, v29
	v_cvt_pk_bf16_f32 v24, v32, v33
	v_cvt_pk_bf16_f32 v25, v30, v31
	ds_write_b128 v26, v[18:21]
	v_add3_u32 v18, v72, v49, v34
	v_mov_b32_e32 v26, 0
	ds_write_b128 v18, v[22:25]
	v_mov_b32_e32 v27, 0
	v_mov_b32_e32 v20, 0
	v_mov_b32_e32 v21, 0
	v_mov_b32_e32 v22, 0
	v_mov_b32_e32 v23, v26
	v_mov_b32_e32 v18, v26
	v_mov_b32_e32 v19, v26
	v_mov_b32_e32 v24, 0
	v_mov_b32_e32 v25, 0
	s_and_saveexec_b64 s[30:31], s[14:15]
	s_cbranch_execz .LBB0_305
	v_add_co_u32_e32 v20, vcc, 0x1000, v56
	v_lshl_add_u64 v[18:19], v[56:57], 0, s[90:91]
	s_nop 0
	v_addc_co_u32_e32 v21, vcc, 0, v57, vcc
	s_nop 0
	v_lshlrev_b32_e32 v18, 16, v14
	v_and_b32_e32 v19, 0xffff0000, v14
	v_lshlrev_b32_e32 v14, 16, v15
	v_and_b32_e32 v15, 0xffff0000, v15
	s_waitcnt vmcnt(0)
	v_pk_fma_f32 v[22:23], v[154:155], v[14:15], 0 op_sel_hi:[1,1,0]
	v_lshlrev_b32_e32 v14, 16, v17
	v_and_b32_e32 v15, 0xffff0000, v17
	v_pk_fma_f32 v[20:21], v[152:153], v[18:19], 0 op_sel_hi:[1,1,0]
	v_lshlrev_b32_e32 v18, 16, v16
	v_and_b32_e32 v19, 0xffff0000, v16
	s_waitcnt vmcnt(0)
	v_pk_fma_f32 v[26:27], v[158:159], v[14:15], 0 op_sel_hi:[1,1,0]
	v_pk_fma_f32 v[18:19], v[156:157], v[18:19], 0 op_sel_hi:[1,1,0]
	v_mov_b32_e32 v24, v26
	v_mov_b32_e32 v25, v27
	s_or_b64 exec, exec, s[30:31]
	s_and_saveexec_b64 s[14:15], s[8:9]
	s_cbranch_execnz .LBB0_306

; DI void unpack8(u32x4 w, float* f) { f[0] = bflo(w.x); f[1] = bfhi(w.x); f[2] = bflo(w.y); f[3] = bfhi(w.y); f[4] = bflo(w.z); f[5] = bfhi(w.z); f[6] = bflo(w.w); f[7] = bfhi(w.w); }
; DI void dn_prep_item(const Params& p, int l, int item, int next_item, u32x4 (&pre)[12], unsigned char* lds, int tid) {
;     ...
;             for (int j = 0; j < 4; ++j) { const int t = n * 64 + i - 3 + j;
;                 if (t >= 0) { float xv[8]; unpack8(pre[mat * 4 + j], xv);
;                     const f32x4 w0 = *(const f32x4*)(cw + j * 1536 + col), w1 = *(const f32x4*)(cw + j * 1536 + col + 4);
; #pragma unroll
;                     for (int e = 0; e < 4; ++e) { a[e] += w0[e] * xv[e]; a[4 + e] += w1[e] * xv[4 + e]; } } }
.LBB0_304:
	s_mov_b64 s[10:11], 0x4000
	v_add_co_u32_e32 v10, vcc, 0x4000, v56
	v_lshl_add_u64 v[14:15], v[56:57], 0, s[10:11]
	s_nop 0
	v_addc_co_u32_e32 v11, vcc, 0, v57, vcc
	s_nop 0
	v_lshlrev_b32_e32 v26, 16, v6
	v_and_b32_e32 v27, 0xffff0000, v6
	v_lshlrev_b32_e32 v6, 16, v7
	v_and_b32_e32 v7, 0xffff0000, v7
	s_waitcnt vmcnt(0)
	v_pk_fma_f32 v[20:21], v[160:161], v[26:27], v[20:21]
	v_lshlrev_b32_e32 v10, 16, v8
	v_and_b32_e32 v11, 0xffff0000, v8
	v_pk_fma_f32 v[22:23], v[162:163], v[6:7], v[22:23]
	v_lshlrev_b32_e32 v6, 16, v9
	v_and_b32_e32 v7, 0xffff0000, v9
	s_waitcnt vmcnt(0)
	v_pk_fma_f32 v[18:19], v[170:171], v[10:11], v[18:19]
	v_pk_fma_f32 v[24:25], v[172:173], v[6:7], v[24:25]
	s_or_b64 exec, exec, s[8:9]
	s_and_saveexec_b64 s[8:9], s[12:13]
	s_cbranch_execnz .LBB0_308
	s_branch .LBB0_309

; DI void unpack8(u32x4 w, float* f) { f[0] = bflo(w.x); f[1] = bfhi(w.x); f[2] = bflo(w.y); f[3] = bfhi(w.y); f[4] = bflo(w.z); f[5] = bfhi(w.z); f[6] = bflo(w.w); f[7] = bfhi(w.w); }
; DI void dn_prep_item(const Params& p, int l, int item, int next_item, u32x4 (&pre)[12], unsigned char* lds, int tid) {
;     ...
;             for (int j = 0; j < 4; ++j) { const int t = n * 64 + i - 3 + j;
;                 if (t >= 0) { float xv[8]; unpack8(pre[mat * 4 + j], xv);
;                     const f32x4 w0 = *(const f32x4*)(cw + j * 1536 + col), w1 = *(const f32x4*)(cw + j * 1536 + col + 4);
; #pragma unroll
;                     for (int e = 0; e < 4; ++e) { a[e] += w0[e] * xv[e]; a[4 + e] += w1[e] * xv[4 + e]; } } }
.LBB0_306:
	v_add_co_u32_e32 v14, vcc, 0x2000, v56
	s_mov_b64 s[8:9], 0x2800
	s_nop 0
	v_addc_co_u32_e32 v15, vcc, 0, v57, vcc
	v_lshl_add_u64 v[24:25], v[56:57], 0, s[8:9]
	s_nop 0
	v_lshlrev_b32_e32 v24, 16, v10
	v_and_b32_e32 v25, 0xffff0000, v10
	v_lshlrev_b32_e32 v10, 16, v11
	v_and_b32_e32 v11, 0xffff0000, v11
	s_waitcnt vmcnt(0)
	v_pk_fma_f32 v[20:21], v[174:175], v[24:25], v[20:21]
	v_lshlrev_b32_e32 v14, 16, v12
	v_and_b32_e32 v15, 0xffff0000, v12
	v_pk_fma_f32 v[22:23], v[176:177], v[10:11], v[22:23]
	v_lshlrev_b32_e32 v10, 16, v13
	v_and_b32_e32 v11, 0xffff0000, v13
	s_waitcnt vmcnt(0)
	v_pk_fma_f32 v[18:19], v[178:179], v[14:15], v[18:19]
	v_pk_fma_f32 v[24:25], v[180:181], v[10:11], v[26:27]
	s_or_b64 exec, exec, s[14:15]
	s_and_saveexec_b64 s[8:9], s[10:11]
	s_cbranch_execnz .LBB0_304

; DI void unpack8(u32x4 w, float* f) { f[0] = bflo(w.x); f[1] = bfhi(w.x); f[2] = bflo(w.y); f[3] = bfhi(w.y); f[4] = bflo(w.z); f[5] = bfhi(w.z); f[6] = bflo(w.w); f[7] = bfhi(w.w); }
; DI void dn_prep_item(const Params& p, int l, int item, int next_item, u32x4 (&pre)[12], unsigned char* lds, int tid) {
;     ...
;             for (int j = 0; j < 4; ++j) { const int t = n * 64 + i - 3 + j;
;                 if (t >= 0) { float xv[8]; unpack8(pre[mat * 4 + j], xv);
;                     const f32x4 w0 = *(const f32x4*)(cw + j * 1536 + col), w1 = *(const f32x4*)(cw + j * 1536 + col + 4);
; #pragma unroll
;                     for (int e = 0; e < 4; ++e) { a[e] += w0[e] * xv[e]; a[4 + e] += w1[e] * xv[4 + e]; } } }
.LBB0_308:
	s_mov_b64 s[10:11], 0x5800
	v_add_co_u32_e32 v6, vcc, 0x5000, v56
	v_lshl_add_u64 v[10:11], v[56:57], 0, s[10:11]
	s_nop 0
	v_addc_co_u32_e32 v7, vcc, 0, v57, vcc
	s_nop 0
	v_lshlrev_b32_e32 v14, 16, v2
	v_and_b32_e32 v15, 0xffff0000, v2
	v_lshlrev_b32_e32 v2, 16, v3
	v_and_b32_e32 v3, 0xffff0000, v3
	s_waitcnt vmcnt(0)
	v_pk_fma_f32 v[20:21], v[182:183], v[14:15], v[20:21]
	v_lshlrev_b32_e32 v6, 16, v4
	v_and_b32_e32 v7, 0xffff0000, v4
	v_pk_fma_f32 v[22:23], v[184:185], v[2:3], v[22:23]
	v_lshlrev_b32_e32 v2, 16, v5
	v_and_b32_e32 v3, 0xffff0000, v5
	s_waitcnt vmcnt(0)
	v_pk_fma_f32 v[18:19], v[186:187], v[6:7], v[18:19]
	v_pk_fma_f32 v[24:25], v[188:189], v[2:3], v[24:25]
